# v51_pin
# speedup vs baseline: 1.0019x; 1.0019x over previous
; template <class Epi, class Sched, bool ALIGN_EPI = false, bool SP2 = false>
; __device__ __forceinline__ void gemm_phase(PG8_LAS unsigned char* lds, const Gemm g, const Sched& S, const Epi& E, const int tid_in) {
;     ...
;         const char* nA = has_next ? (const char*)g.A + (size_t)nxt.pm * tstep : cA; const char* nB = has_next ? (const char*)g.Bt + (size_t)nxt.pn * tstep : cB;
;         for (int t = 0; t < nt; t += 2) {
;             const bool last = (t == nt - 2);
;             const char* a1 = cA + (size_t)(t + 1) * kstep;
;             const char* a2 = last ? nA : cA + (size_t)(t + 2) * kstep; const char* b2 = last ? nB : cB + (size_t)(t + 2) * kstep;
;             const char* a3 = a2 + kstep; const char* b3 = b2 + kstep;
;     ...
;         for (int a = 0; a < 2; ++a)
; #pragma unroll
;             for (int b = 0; b < 2; ++b)
; #pragma unroll
;                 for (int m = 0; m < 4; ++m)
; #pragma unroll
;                     for (int n = 0; n < 2; ++n) acc[a][b][m][n] = (f32x4){0.f, 0.f, 0.f, 0.f};
.LBB0_24:
	s_ashr_i32 s25, s24, 31
	s_lshl_b64 s[26:27], s[24:25], 20
	s_add_u32 s26, s48, s26
	s_addc_u32 s27, s49, s27
	s_and_b64 s[36:37], s[6:7], exec
	s_cselect_b32 s25, s27, s41
	s_cselect_b32 s72, s26, s40
	s_ashr_i32 s17, s16, 31
	s_lshl_b64 s[36:37], s[16:17], 20
	s_add_u32 s36, s46, s36
	s_addc_u32 s37, s47, s37
	s_and_b64 s[44:45], s[6:7], exec
	s_cselect_b32 s17, s37, s43
	s_cselect_b32 s83, s36, s42
	s_add_u32 s40, s40, 0x80080
	s_addc_u32 s41, s41, 0
	s_add_u32 s84, s42, 0x100
	v_mov_b32_e32 v2, 0
	s_addc_u32 s85, s43, 0
	s_mov_b32 s86, -2
	v_mov_b32_e32 v3, v2
	v_mov_b32_e32 v4, v2
	v_mov_b32_e32 v5, v2
	v_mov_b32_e32 v10, v2
	v_mov_b32_e32 v11, v2
	v_mov_b32_e32 v12, v2
	v_mov_b32_e32 v13, v2
	v_mov_b32_e32 v18, v2
	v_mov_b32_e32 v19, v2
	v_mov_b32_e32 v20, v2
	v_mov_b32_e32 v21, v2
	v_mov_b32_e32 v26, v2
	v_mov_b32_e32 v27, v2
	v_mov_b32_e32 v28, v2
	v_mov_b32_e32 v29, v2
	v_mov_b32_e32 v34, v2
	v_mov_b32_e32 v35, v2
	v_mov_b32_e32 v36, v2
	v_mov_b32_e32 v37, v2
	v_mov_b32_e32 v42, v2
	v_mov_b32_e32 v43, v2
	v_mov_b32_e32 v44, v2
	v_mov_b32_e32 v45, v2
	v_mov_b32_e32 v50, v2
	v_mov_b32_e32 v51, v2
	v_mov_b32_e32 v52, v2
	v_mov_b32_e32 v53, v2
	v_mov_b32_e32 v58, v2
	v_mov_b32_e32 v59, v2
	v_mov_b32_e32 v60, v2
	v_mov_b32_e32 v61, v2
	v_mov_b32_e32 v6, v2
	v_mov_b32_e32 v7, v2
	v_mov_b32_e32 v8, v2
	v_mov_b32_e32 v9, v2
	v_mov_b32_e32 v14, v2
	v_mov_b32_e32 v15, v2
	v_mov_b32_e32 v16, v2
	v_mov_b32_e32 v17, v2
	v_mov_b32_e32 v22, v2
	v_mov_b32_e32 v23, v2
	v_mov_b32_e32 v24, v2
	v_mov_b32_e32 v25, v2
	v_mov_b32_e32 v30, v2
	v_mov_b32_e32 v31, v2
	v_mov_b32_e32 v32, v2
	v_mov_b32_e32 v33, v2
	v_mov_b32_e32 v38, v2
	v_mov_b32_e32 v39, v2
	v_mov_b32_e32 v40, v2
	v_mov_b32_e32 v41, v2
	v_mov_b32_e32 v46, v2
	v_mov_b32_e32 v47, v2
	v_mov_b32_e32 v48, v2
	v_mov_b32_e32 v49, v2
	v_mov_b32_e32 v54, v2
	v_mov_b32_e32 v55, v2
	v_mov_b32_e32 v56, v2
	v_mov_b32_e32 v57, v2
	v_mov_b32_e32 v62, v2
	v_mov_b32_e32 v63, v2
	v_mov_b32_e32 v64, v2
	v_mov_b32_e32 v65, v2
	v_mov_b32_e32 v66, v2
	v_mov_b32_e32 v67, v2
	v_mov_b32_e32 v68, v2
	v_mov_b32_e32 v69, v2
	v_mov_b32_e32 v74, v2
	v_mov_b32_e32 v75, v2
	v_mov_b32_e32 v76, v2
	v_mov_b32_e32 v77, v2
	v_mov_b32_e32 v82, v2
	v_mov_b32_e32 v83, v2
	v_mov_b32_e32 v84, v2
	v_mov_b32_e32 v85, v2
	v_mov_b32_e32 v90, v2
	v_mov_b32_e32 v91, v2
	v_mov_b32_e32 v92, v2
	v_mov_b32_e32 v93, v2
	v_mov_b32_e32 v98, v2
	v_mov_b32_e32 v99, v2
	v_mov_b32_e32 v100, v2
	v_mov_b32_e32 v101, v2
	v_mov_b32_e32 v106, v2
	v_mov_b32_e32 v107, v2
	v_mov_b32_e32 v108, v2
	v_mov_b32_e32 v109, v2
	v_mov_b32_e32 v114, v2
	v_mov_b32_e32 v115, v2
	v_mov_b32_e32 v116, v2
	v_mov_b32_e32 v117, v2
	v_mov_b32_e32 v122, v2
	v_mov_b32_e32 v123, v2
	v_mov_b32_e32 v124, v2
	v_mov_b32_e32 v125, v2
	v_mov_b32_e32 v70, v2
	v_mov_b32_e32 v71, v2
	v_mov_b32_e32 v72, v2
	v_mov_b32_e32 v73, v2
	v_mov_b32_e32 v78, v2
	v_mov_b32_e32 v79, v2
	v_mov_b32_e32 v80, v2
	v_mov_b32_e32 v81, v2
	v_mov_b32_e32 v86, v2
	v_mov_b32_e32 v87, v2
	v_mov_b32_e32 v88, v2
	v_mov_b32_e32 v89, v2
	v_mov_b32_e32 v94, v2
	v_mov_b32_e32 v95, v2
	v_mov_b32_e32 v96, v2
	v_mov_b32_e32 v97, v2
	v_mov_b32_e32 v102, v2
	v_mov_b32_e32 v103, v2
	v_mov_b32_e32 v104, v2
	v_mov_b32_e32 v105, v2
	v_mov_b32_e32 v110, v2
	v_mov_b32_e32 v111, v2
	v_mov_b32_e32 v112, v2
	v_mov_b32_e32 v113, v2
	v_mov_b32_e32 v118, v2
	v_mov_b32_e32 v119, v2
	v_mov_b32_e32 v120, v2
	v_mov_b32_e32 v121, v2
	v_mov_b32_e32 v126, v2
	v_mov_b32_e32 v127, v2
	v_mov_b32_e32 v128, v2
	v_mov_b32_e32 v129, v2
	s_nop 0
	s_nop 0
	s_nop 0
	s_nop 0
	s_nop 0
	s_nop 0
	s_nop 0
	s_nop 0
	s_nop 0
	s_nop 0
	s_nop 0
	s_nop 0
	s_nop 0
	s_nop 0
	s_nop 0
	s_nop 0
	s_nop 0
	s_nop 0
	s_nop 0
	s_nop 0
	s_nop 0
	s_nop 0
	s_nop 0
	s_nop 0
	s_nop 0
	s_nop 0
	s_nop 0
	s_nop 0
	s_nop 0
	s_nop 0
	s_nop 0

; template <class Epi, class Sched, bool ALIGN_EPI = false, bool SP2 = false>
; __device__ __forceinline__ void gemm_phase(PG8_LAS unsigned char* lds, const Gemm g, const Sched& S, const Epi& E, const int tid_in) {
;     ...
;         const char* nA = has_next ? (const char*)g.A + (size_t)nxt.pm * tstep : cA; const char* nB = has_next ? (const char*)g.Bt + (size_t)nxt.pn * tstep : cB;
;         for (int t = 0; t < nt; t += 2) {
;             const bool last = (t == nt - 2);
;             const char* a1 = cA + (size_t)(t + 1) * kstep;
;             const char* a2 = last ? nA : cA + (size_t)(t + 2) * kstep; const char* b2 = last ? nB : cB + (size_t)(t + 2) * kstep;
;             const char* a3 = a2 + kstep; const char* b3 = b2 + kstep;
;     ...
;         for (int a = 0; a < 2; ++a)
; #pragma unroll
;             for (int b = 0; b < 2; ++b)
; #pragma unroll
;                 for (int m = 0; m < 4; ++m)
; #pragma unroll
;                     for (int n = 0; n < 2; ++n) acc[a][b][m][n] = (f32x4){0.f, 0.f, 0.f, 0.f};
.LBB0_57:
	s_ashr_i32 s37, s36, 31
	s_lshl_b64 s[38:39], s[36:37], 20
	s_add_u32 s38, s53, s38
	s_addc_u32 s39, s54, s39
	s_and_b64 s[40:41], s[6:7], exec
	s_cselect_b32 s37, s39, s45
	s_cselect_b32 s72, s38, s44
	s_ashr_i32 s27, s26, 31
	s_lshl_b64 s[40:41], s[26:27], 20
	s_add_u32 s40, s34, s40
	s_addc_u32 s41, s52, s41
	s_and_b64 s[48:49], s[6:7], exec
	s_cselect_b32 s27, s41, s47
	s_cselect_b32 s87, s40, s46
	s_add_u32 s88, s46, 0x100
	v_mov_b32_e32 v2, 0
	s_addc_u32 s89, s47, 0
	s_mov_b32 vcc_lo, -2
	v_mov_b32_e32 v3, v2
	v_mov_b32_e32 v4, v2
	v_mov_b32_e32 v5, v2
	v_mov_b32_e32 v6, v2
	v_mov_b32_e32 v7, v2
	v_mov_b32_e32 v8, v2
	v_mov_b32_e32 v9, v2
	v_mov_b32_e32 v14, v2
	v_mov_b32_e32 v15, v2
	v_mov_b32_e32 v16, v2
	v_mov_b32_e32 v17, v2
	v_mov_b32_e32 v18, v2
	v_mov_b32_e32 v19, v2
	v_mov_b32_e32 v20, v2
	v_mov_b32_e32 v21, v2
	v_mov_b32_e32 v30, v2
	v_mov_b32_e32 v31, v2
	v_mov_b32_e32 v32, v2
	v_mov_b32_e32 v33, v2
	v_mov_b32_e32 v34, v2
	v_mov_b32_e32 v35, v2
	v_mov_b32_e32 v36, v2
	v_mov_b32_e32 v37, v2
	v_mov_b32_e32 v46, v2
	v_mov_b32_e32 v47, v2
	v_mov_b32_e32 v48, v2
	v_mov_b32_e32 v49, v2
	v_mov_b32_e32 v50, v2
	v_mov_b32_e32 v51, v2
	v_mov_b32_e32 v52, v2
	v_mov_b32_e32 v53, v2
	v_mov_b32_e32 v10, v2
	v_mov_b32_e32 v11, v2
	v_mov_b32_e32 v12, v2
	v_mov_b32_e32 v13, v2
	v_mov_b32_e32 v22, v2
	v_mov_b32_e32 v23, v2
	v_mov_b32_e32 v24, v2
	v_mov_b32_e32 v25, v2
	v_mov_b32_e32 v26, v2
	v_mov_b32_e32 v27, v2
	v_mov_b32_e32 v28, v2
	v_mov_b32_e32 v29, v2
	v_mov_b32_e32 v38, v2
	v_mov_b32_e32 v39, v2
	v_mov_b32_e32 v40, v2
	v_mov_b32_e32 v41, v2
	v_mov_b32_e32 v42, v2
	v_mov_b32_e32 v43, v2
	v_mov_b32_e32 v44, v2
	v_mov_b32_e32 v45, v2
	v_mov_b32_e32 v54, v2
	v_mov_b32_e32 v55, v2
	v_mov_b32_e32 v56, v2
	v_mov_b32_e32 v57, v2
	v_mov_b32_e32 v58, v2
	v_mov_b32_e32 v59, v2
	v_mov_b32_e32 v60, v2
	v_mov_b32_e32 v61, v2
	v_mov_b32_e32 v62, v2
	v_mov_b32_e32 v63, v2
	v_mov_b32_e32 v64, v2
	v_mov_b32_e32 v65, v2
	v_mov_b32_e32 v66, v2
	v_mov_b32_e32 v67, v2
	v_mov_b32_e32 v68, v2
	v_mov_b32_e32 v69, v2
	v_mov_b32_e32 v70, v2
	v_mov_b32_e32 v71, v2
	v_mov_b32_e32 v72, v2
	v_mov_b32_e32 v73, v2
	v_mov_b32_e32 v78, v2
	v_mov_b32_e32 v79, v2
	v_mov_b32_e32 v80, v2
	v_mov_b32_e32 v81, v2
	v_mov_b32_e32 v82, v2
	v_mov_b32_e32 v83, v2
	v_mov_b32_e32 v84, v2
	v_mov_b32_e32 v85, v2
	v_mov_b32_e32 v94, v2
	v_mov_b32_e32 v95, v2
	v_mov_b32_e32 v96, v2
	v_mov_b32_e32 v97, v2
	v_mov_b32_e32 v98, v2
	v_mov_b32_e32 v99, v2
	v_mov_b32_e32 v100, v2
	v_mov_b32_e32 v101, v2
	v_mov_b32_e32 v110, v2
	v_mov_b32_e32 v111, v2
	v_mov_b32_e32 v112, v2
	v_mov_b32_e32 v113, v2
	v_mov_b32_e32 v114, v2
	v_mov_b32_e32 v115, v2
	v_mov_b32_e32 v116, v2
	v_mov_b32_e32 v117, v2
	v_mov_b32_e32 v74, v2
	v_mov_b32_e32 v75, v2
	v_mov_b32_e32 v76, v2
	v_mov_b32_e32 v77, v2
	v_mov_b32_e32 v86, v2
	v_mov_b32_e32 v87, v2
	v_mov_b32_e32 v88, v2
	v_mov_b32_e32 v89, v2
	v_mov_b32_e32 v90, v2
	v_mov_b32_e32 v91, v2
	v_mov_b32_e32 v92, v2
	v_mov_b32_e32 v93, v2
	v_mov_b32_e32 v102, v2
	v_mov_b32_e32 v103, v2
	v_mov_b32_e32 v104, v2
	v_mov_b32_e32 v105, v2
	v_mov_b32_e32 v106, v2
	v_mov_b32_e32 v107, v2
	v_mov_b32_e32 v108, v2
	v_mov_b32_e32 v109, v2
	v_mov_b32_e32 v118, v2
	v_mov_b32_e32 v119, v2
	v_mov_b32_e32 v120, v2
	v_mov_b32_e32 v121, v2
	v_mov_b32_e32 v122, v2
	v_mov_b32_e32 v123, v2
	v_mov_b32_e32 v124, v2
	v_mov_b32_e32 v125, v2
	v_mov_b32_e32 v126, v2
	v_mov_b32_e32 v127, v2
	v_mov_b32_e32 v128, v2
	v_mov_b32_e32 v129, v2
	s_nop 0
	s_nop 0
	s_nop 0
	s_nop 0
	s_nop 0
	s_nop 0

; template <class Epi, class Sched, bool ALIGN_EPI = false, bool SP2 = false>
; __device__ __forceinline__ void gemm_phase(PG8_LAS unsigned char* lds, const Gemm g, const Sched& S, const Epi& E, const int tid_in) {
;     ...
;         for (int a = 0; a < 2; ++a)
; #pragma unroll
;             for (int b = 0; b < 2; ++b)
; #pragma unroll
;                 for (int m = 0; m < 4; ++m)
; #pragma unroll
;                     for (int n = 0; n < 2; ++n) acc[a][b][m][n] = (f32x4){0.f, 0.f, 0.f, 0.f};
;         cur = nxt; cA = nA; cB = nB; ++ui;
.Lrb_nozero:
	s_nop 0
	s_nop 0
	s_nop 0
	s_nop 0
	s_nop 0
	s_nop 0
	s_nop 0
	s_nop 0
	s_nop 0
	s_nop 0
	s_nop 0
	s_nop 0
	s_nop 0
	s_nop 0
	s_nop 0
	s_nop 0
	s_nop 0
	s_nop 0
	s_nop 0
	s_nop 0
	s_nop 0
	s_nop 0
	s_nop 0
	s_nop 0
	s_nop 0
	s_nop 0
	s_nop 0
	s_nop 0
	s_nop 0
	s_nop 0

; template <class Epi, class Sched, bool ALIGN_EPI = false, bool SP2 = false>
; __device__ __forceinline__ void gemm_phase(PG8_LAS unsigned char* lds, const Gemm g, const Sched& S, const Epi& E, const int tid_in) {
;     ...
;         const char* nA = has_next ? (const char*)g.A + (size_t)nxt.pm * tstep : cA; const char* nB = has_next ? (const char*)g.Bt + (size_t)nxt.pn * tstep : cB;
;         for (int t = 0; t < nt; t += 2) {
;             const bool last = (t == nt - 2);
;             const char* a1 = cA + (size_t)(t + 1) * kstep;
;             const char* a2 = last ? nA : cA + (size_t)(t + 2) * kstep; const char* b2 = last ? nB : cB + (size_t)(t + 2) * kstep;
;             const char* a3 = a2 + kstep; const char* b3 = b2 + kstep;
;     ...
;         for (int a = 0; a < 2; ++a)
; #pragma unroll
;             for (int b = 0; b < 2; ++b)
; #pragma unroll
;                 for (int m = 0; m < 4; ++m)
; #pragma unroll
;                     for (int n = 0; n < 2; ++n) acc[a][b][m][n] = (f32x4){0.f, 0.f, 0.f, 0.f};
.LBB0_1185:
	s_ashr_i32 s37, s36, 31
	s_lshl_b64 s[38:39], s[36:37], 20
	s_add_u32 s38, s25, s38
	s_addc_u32 s39, s34, s39
	s_and_b64 s[40:41], s[6:7], exec
	s_cselect_b32 s9, s39, s45
	s_cselect_b32 s37, s38, s44
	s_ashr_i32 s27, s26, 31
	s_lshl_b64 s[40:41], s[26:27], 20
	s_add_u32 s40, s10, s40
	s_addc_u32 s41, s11, s41
	s_and_b64 s[48:49], s[6:7], exec
	s_cselect_b32 s27, s41, s47
	s_cselect_b32 s72, s40, s46
	s_add_u32 s44, s44, 0x80080
	s_addc_u32 s45, s45, 0
	s_add_u32 s73, s46, 0x100
	v_mov_b32_e32 v2, 0
	s_addc_u32 s83, s47, 0
	s_mov_b32 s84, -2
	v_mov_b32_e32 v3, v2
	v_mov_b32_e32 v4, v2
	v_mov_b32_e32 v5, v2
	v_mov_b32_e32 v6, v2
	v_mov_b32_e32 v7, v2
	v_mov_b32_e32 v8, v2
	v_mov_b32_e32 v9, v2
	v_mov_b32_e32 v14, v2
	v_mov_b32_e32 v15, v2
	v_mov_b32_e32 v16, v2
	v_mov_b32_e32 v17, v2
	v_mov_b32_e32 v22, v2
	v_mov_b32_e32 v23, v2
	v_mov_b32_e32 v24, v2
	v_mov_b32_e32 v25, v2
	v_mov_b32_e32 v30, v2
	v_mov_b32_e32 v31, v2
	v_mov_b32_e32 v32, v2
	v_mov_b32_e32 v33, v2
	v_mov_b32_e32 v38, v2
	v_mov_b32_e32 v39, v2
	v_mov_b32_e32 v40, v2
	v_mov_b32_e32 v41, v2
	v_mov_b32_e32 v46, v2
	v_mov_b32_e32 v47, v2
	v_mov_b32_e32 v48, v2
	v_mov_b32_e32 v49, v2
	v_mov_b32_e32 v54, v2
	v_mov_b32_e32 v55, v2
	v_mov_b32_e32 v56, v2
	v_mov_b32_e32 v57, v2
	v_mov_b32_e32 v10, v2
	v_mov_b32_e32 v11, v2
	v_mov_b32_e32 v12, v2
	v_mov_b32_e32 v13, v2
	v_mov_b32_e32 v18, v2
	v_mov_b32_e32 v19, v2
	v_mov_b32_e32 v20, v2
	v_mov_b32_e32 v21, v2
	v_mov_b32_e32 v26, v2
	v_mov_b32_e32 v27, v2
	v_mov_b32_e32 v28, v2
	v_mov_b32_e32 v29, v2
	v_mov_b32_e32 v34, v2
	v_mov_b32_e32 v35, v2
	v_mov_b32_e32 v36, v2
	v_mov_b32_e32 v37, v2
	v_mov_b32_e32 v42, v2
	v_mov_b32_e32 v43, v2
	v_mov_b32_e32 v44, v2
	v_mov_b32_e32 v45, v2
	v_mov_b32_e32 v50, v2
	v_mov_b32_e32 v51, v2
	v_mov_b32_e32 v52, v2
	v_mov_b32_e32 v53, v2
	v_mov_b32_e32 v58, v2
	v_mov_b32_e32 v59, v2
	v_mov_b32_e32 v60, v2
	v_mov_b32_e32 v61, v2
	v_mov_b32_e32 v62, v2
	v_mov_b32_e32 v63, v2
	v_mov_b32_e32 v64, v2
	v_mov_b32_e32 v65, v2
	v_mov_b32_e32 v66, v2
	v_mov_b32_e32 v67, v2
	v_mov_b32_e32 v68, v2
	v_mov_b32_e32 v69, v2
	v_mov_b32_e32 v70, v2
	v_mov_b32_e32 v71, v2
	v_mov_b32_e32 v72, v2
	v_mov_b32_e32 v73, v2
	v_mov_b32_e32 v78, v2
	v_mov_b32_e32 v79, v2
	v_mov_b32_e32 v80, v2
	v_mov_b32_e32 v81, v2
	v_mov_b32_e32 v86, v2
	v_mov_b32_e32 v87, v2
	v_mov_b32_e32 v88, v2
	v_mov_b32_e32 v89, v2
	v_mov_b32_e32 v94, v2
	v_mov_b32_e32 v95, v2
	v_mov_b32_e32 v96, v2
	v_mov_b32_e32 v97, v2
	v_mov_b32_e32 v102, v2
	v_mov_b32_e32 v103, v2
	v_mov_b32_e32 v104, v2
	v_mov_b32_e32 v105, v2
	v_mov_b32_e32 v110, v2
	v_mov_b32_e32 v111, v2
	v_mov_b32_e32 v112, v2
	v_mov_b32_e32 v113, v2
	v_mov_b32_e32 v118, v2
	v_mov_b32_e32 v119, v2
	v_mov_b32_e32 v120, v2
	v_mov_b32_e32 v121, v2
	v_mov_b32_e32 v74, v2
	v_mov_b32_e32 v75, v2
	v_mov_b32_e32 v76, v2
	v_mov_b32_e32 v77, v2
	v_mov_b32_e32 v82, v2
	v_mov_b32_e32 v83, v2
	v_mov_b32_e32 v84, v2
	v_mov_b32_e32 v85, v2
	v_mov_b32_e32 v90, v2
	v_mov_b32_e32 v91, v2
	v_mov_b32_e32 v92, v2
	v_mov_b32_e32 v93, v2
	v_mov_b32_e32 v98, v2
	v_mov_b32_e32 v99, v2
	v_mov_b32_e32 v100, v2
	v_mov_b32_e32 v101, v2
	v_mov_b32_e32 v106, v2
	v_mov_b32_e32 v107, v2
	v_mov_b32_e32 v108, v2
	v_mov_b32_e32 v109, v2
	v_mov_b32_e32 v114, v2
	v_mov_b32_e32 v115, v2
	v_mov_b32_e32 v116, v2
	v_mov_b32_e32 v117, v2
	v_mov_b32_e32 v122, v2
	v_mov_b32_e32 v123, v2
	v_mov_b32_e32 v124, v2
	v_mov_b32_e32 v125, v2
	v_mov_b32_e32 v126, v2
	v_mov_b32_e32 v127, v2
	v_mov_b32_e32 v128, v2
	v_mov_b32_e32 v129, v2
	s_nop 0
	s_nop 0
	s_nop 0
	s_nop 0
	s_nop 0
	s_nop 0
